# v36 + P0 rmsnorm rows: loop-invariant gain vector loaded once before the row loop; the per-chunk (load gain, s_waitcnt vmcnt(0), store) serial chain in each row is gone
# speedup vs baseline: 1.0063x; 1.0063x over previous
; DI unsigned pk2(float lo, float hi) { f32x2 v = {lo, hi}; return __builtin_bit_cast(unsigned, __builtin_convertvector(v, bf16x2v)); }
; DI void rms_row(const float* xrow, const float* g, bf16_t* orow, int lane) {
;     f32x4 v[8]; float s = 0.f;
; #pragma unroll
;     for (int j = 0; j < 8; ++j) { v[j] = __builtin_nontemporal_load((const f32x4*)xrow + lane + 64 * j); s += (v[j][0] * v[j][0] + v[j][1] * v[j][1]) + (v[j][2] * v[j][2] + v[j][3] * v[j][3]); }
;     const float rstd = rsqrtf(wave_sum(s) * (1.0f / DM) + EPS);
; #pragma unroll
;     for (int j = 0; j < 8; ++j) { const f32x4 gg = *((const f32x4*)g + lane + 64 * j); u32x2 o; o.x = pk2(v[j][0] * rstd * gg[0], v[j][1] * rstd * gg[1]); o.y = pk2(v[j][2] * rstd * gg[2], v[j][3] * rstd * gg[3]);
; __global__ void __launch_bounds__(512, 2) fwd_kernel(Args a) {
;     ...
;         for (int m = gw; m < MP; m += NGW) {
;             if (m < MR) rms_row(m < LP ? x_p + (size_t)m * DM : x_s + (size_t)(m - LP) * DM, ln1_g, H1 + (size_t)m * DM, lane);
.LBB0_25:
	s_cmpk_gt_i32 s10, 0x20ff
	s_cbranch_scc1 .LBB0_34
	v_mov_b32_e32 v13, 0
	v_lshlrev_b32_e32 v12, 3, v152
	v_lshl_add_u64 v[14:15], s[66:67], 0, v[12:13]
	v_lshlrev_b32_e32 v12, 4, v152
	s_waitcnt lgkmcnt(0)
	v_lshl_add_u64 v[16:17], s[54:55], 0, v[12:13]
	s_mov_b64 s[2:3], 0x1000
	v_lshl_add_u64 v[18:19], v[16:17], 0, s[2:3]
	s_mov_b64 s[2:3], 0x1400
	v_lshl_add_u64 v[20:21], v[16:17], 0, s[2:3]
	s_mov_b64 s[2:3], 0x1800
	v_lshl_add_u64 v[22:23], v[16:17], 0, s[2:3]
	s_mov_b64 s[2:3], 0x1c00
	s_ashr_i32 s11, s10, 31
	v_mbcnt_lo_u32_b32 v0, -1, 0
	v_lshl_add_u64 v[24:25], v[16:17], 0, s[2:3]
	s_ashr_i32 s13, s12, 31
	s_lshl_b64 s[2:3], s[10:11], 13
	v_mbcnt_hi_u32_b32 v27, -1, v0
	s_add_u32 s2, s44, s2
	v_and_b32_e32 v0, 64, v27
	s_addc_u32 s3, s45, s3
	s_lshl_b64 s[4:5], s[12:13], 13
	s_mov_b32 s15, 0
	v_lshlrev_b32_e32 v12, 4, v152
	s_movk_i32 s20, 0x1000
	v_mov_b32_e32 v26, 0x358637bd
	s_mov_b32 s21, 0x800000
	v_add_u32_e32 v28, 64, v0
	v_xor_b32_e32 v29, 1, v27
	v_xor_b32_e32 v30, 2, v27
	v_xor_b32_e32 v31, 4, v27
	v_xor_b32_e32 v32, 8, v27
	v_xor_b32_e32 v33, 16, v27
	v_xor_b32_e32 v34, 32, v27
	global_load_dwordx4 v[96:99], v[16:17], off
	global_load_dwordx4 v[100:103], v[16:17], off offset:1024
	global_load_dwordx4 v[104:107], v[16:17], off offset:2048
	global_load_dwordx4 v[108:111], v[16:17], off offset:3072
	global_load_dwordx4 v[112:115], v[18:19], off
	global_load_dwordx4 v[116:119], v[20:21], off
	global_load_dwordx4 v[120:123], v[22:23], off
	global_load_dwordx4 v[124:127], v[24:25], off
	s_branch .LBB0_29
; DI unsigned pk2(float lo, float hi) { f32x2 v = {lo, hi}; return __builtin_bit_cast(unsigned, __builtin_convertvector(v, bf16x2v)); }
; DI void rms_row(const float* xrow, const float* g, bf16_t* orow, int lane) {
;     f32x4 v[8]; float s = 0.f;
; #pragma unroll
;     for (int j = 0; j < 8; ++j) { v[j] = __builtin_nontemporal_load((const f32x4*)xrow + lane + 64 * j); s += (v[j][0] * v[j][0] + v[j][1] * v[j][1]) + (v[j][2] * v[j][2] + v[j][3] * v[j][3]); }
;     const float rstd = rsqrtf(wave_sum(s) * (1.0f / DM) + EPS);
; #pragma unroll
;     for (int j = 0; j < 8; ++j) { const f32x4 gg = *((const f32x4*)g + lane + 64 * j); u32x2 o; o.x = pk2(v[j][0] * rstd * gg[0], v[j][1] * rstd * gg[1]); o.y = pk2(v[j][2] * rstd * gg[2], v[j][3] * rstd * gg[3]);
;         *((u32x2*)orow + lane + 64 * j) = o; }
; }
.LBB0_27:
	global_load_dwordx4 v[36:39], v12, s[18:19] nt
	global_load_dwordx4 v[8:11], v12, s[18:19] offset:1024 nt
	global_load_dwordx4 v[40:43], v12, s[18:19] offset:2048 nt
	global_load_dwordx4 v[44:47], v12, s[18:19] offset:3072 nt
	v_lshl_add_u64 v[0:1], s[18:19], 0, v[12:13]
	v_add_co_u32_e32 v56, vcc, s20, v0
	s_lshl_b64 s[16:17], s[16:17], 12
	s_nop 0
	v_addc_co_u32_e32 v57, vcc, 0, v1, vcc
	global_load_dwordx4 v[4:7], v[56:57], off nt
	global_load_dwordx4 v[48:51], v[56:57], off offset:1024 nt
	global_load_dwordx4 v[0:3], v[56:57], off offset:3072 nt
	global_load_dwordx4 v[52:55], v[56:57], off offset:2048 nt
	v_cmp_lt_i32_e32 vcc, v29, v28
	s_waitcnt vmcnt(7)
	v_mov_b32_e32 v62, v37
	s_waitcnt vmcnt(6)
	v_mov_b32_e32 v63, v9
	v_mov_b32_e32 v66, v39
	v_mov_b32_e32 v67, v11
	v_mov_b32_e32 v60, v36
	v_mov_b32_e32 v61, v8
	v_mov_b32_e32 v64, v38
	v_mov_b32_e32 v65, v10
	s_waitcnt vmcnt(5)
	v_pk_mul_f32 v[68:69], v[42:43], v[42:43]
	v_pk_mul_f32 v[70:71], v[40:41], v[40:41]
	v_pk_mul_f32 v[62:63], v[62:63], v[62:63]
	v_pk_mul_f32 v[66:67], v[66:67], v[66:67]
	v_pk_mov_b32 v[76:77], v[70:71], v[68:69] op_sel:[1,0]
	v_mov_b32_e32 v71, v69
	v_pk_fma_f32 v[60:61], v[60:61], v[60:61], v[62:63]
	v_pk_fma_f32 v[62:63], v[64:65], v[64:65], v[66:67]
	s_waitcnt vmcnt(4)
	v_mul_f32_e32 v72, v45, v45
	v_mul_f32_e32 v74, v47, v47
	v_pk_add_f32 v[64:65], v[76:77], v[70:71]
	v_pk_add_f32 v[60:61], v[60:61], v[62:63]
	v_pk_fma_f32 v[68:69], v[44:45], v[44:45], v[72:73] op_sel_hi:[1,1,0]
	v_pk_fma_f32 v[72:73], v[46:47], v[46:47], v[74:75] op_sel_hi:[1,1,0]
	s_waitcnt vmcnt(3)
	v_mul_f32_e32 v77, v4, v4
	v_mul_f32_e32 v78, v5, v5
	v_pk_add_f32 v[62:63], v[64:65], v[64:65] op_sel:[0,1] op_sel_hi:[1,0]
	v_pk_add_f32 v[60:61], v[60:61], v[60:61] op_sel:[0,1] op_sel_hi:[1,0]
	v_mul_f32_e32 v69, v6, v6
	v_mul_f32_e32 v73, v7, v7
	s_waitcnt vmcnt(2)
	v_pk_mul_f32 v[66:67], v[50:51], v[50:51]
	v_pk_mul_f32 v[70:71], v[48:49], v[48:49]
	v_mov_b32_e32 v63, v78
	v_mov_b32_e32 v61, v77
	v_pk_mov_b32 v[64:65], v[70:71], v[66:67] op_sel:[1,0]
	v_mov_b32_e32 v71, v67
	v_pk_add_f32 v[68:69], v[68:69], v[72:73]
	v_pk_add_f32 v[60:61], v[60:61], v[62:63]
	s_waitcnt vmcnt(0)
	v_mul_f32_e32 v74, v53, v53
	v_mul_f32_e32 v76, v55, v55
	v_pk_add_f32 v[64:65], v[64:65], v[70:71]
	v_pk_add_f32 v[60:61], v[60:61], v[68:69]
	v_mul_f32_e32 v79, v0, v0
	v_mul_f32_e32 v80, v1, v1
	v_mul_f32_e32 v81, v2, v2
	v_mul_f32_e32 v82, v3, v3
	v_pk_fma_f32 v[66:67], v[52:53], v[52:53], v[74:75] op_sel_hi:[1,1,0]
	v_pk_fma_f32 v[74:75], v[54:55], v[54:55], v[76:77] op_sel_hi:[1,1,0]
	v_pk_add_f32 v[64:65], v[64:65], v[64:65] op_sel:[0,1] op_sel_hi:[1,0]
	v_pk_add_f32 v[60:61], v[60:61], v[60:61] op_sel:[0,1] op_sel_hi:[1,0]
	v_mov_b32_e32 v67, v81
	v_mov_b32_e32 v75, v82
	v_mov_b32_e32 v65, v80
	v_mov_b32_e32 v61, v79
	v_pk_add_f32 v[66:67], v[66:67], v[74:75]
	v_pk_add_f32 v[60:61], v[60:61], v[64:65]
	v_cndmask_b32_e32 v35, v27, v29, vcc
	v_pk_add_f32 v[60:61], v[60:61], v[66:67]
	v_lshlrev_b32_e32 v35, 2, v35
	v_add_f32_e32 v60, v60, v61
	ds_bpermute_b32 v35, v35, v60
	v_cmp_lt_i32_e32 vcc, v30, v28
	s_waitcnt lgkmcnt(0)
	v_add_f32_e32 v35, v60, v35
	v_cndmask_b32_e32 v61, v27, v30, vcc
	v_lshlrev_b32_e32 v61, 2, v61
	ds_bpermute_b32 v60, v61, v35
	v_cmp_lt_i32_e32 vcc, v31, v28
	s_waitcnt lgkmcnt(0)
	v_add_f32_e32 v35, v35, v60
	v_cndmask_b32_e32 v61, v27, v31, vcc
	v_lshlrev_b32_e32 v61, 2, v61
	ds_bpermute_b32 v60, v61, v35
	v_cmp_lt_i32_e32 vcc, v32, v28
	s_waitcnt lgkmcnt(0)
	v_add_f32_e32 v35, v35, v60
	v_cndmask_b32_e32 v61, v27, v32, vcc
	v_lshlrev_b32_e32 v61, 2, v61
	ds_bpermute_b32 v60, v61, v35
	v_cmp_lt_i32_e32 vcc, v33, v28
	s_waitcnt lgkmcnt(0)
	v_add_f32_e32 v35, v35, v60
	v_cndmask_b32_e32 v61, v27, v33, vcc
	v_lshlrev_b32_e32 v61, 2, v61
	ds_bpermute_b32 v60, v61, v35
	v_cmp_lt_i32_e32 vcc, v34, v28
	s_waitcnt lgkmcnt(0)
	v_add_f32_e32 v35, v35, v60
	v_cndmask_b32_e32 v61, v27, v34, vcc
	v_lshlrev_b32_e32 v61, 2, v61
	ds_bpermute_b32 v60, v61, v35
	s_waitcnt lgkmcnt(0)
	v_add_f32_e32 v35, v35, v60
	v_fmamk_f32 v35, v35, 0x3a000000, v26
	v_mul_f32_e32 v60, 0x4b800000, v35
	v_cmp_gt_f32_e32 vcc, s21, v35
	s_nop 1
	v_cndmask_b32_e32 v35, v35, v60, vcc
	v_rsq_f32_e32 v35, v35
	v_lshl_add_u64 v[60:61], v[14:15], 0, s[16:17]
	v_mul_f32_e32 v62, 0x45800000, v35
	v_cndmask_b32_e32 v62, v35, v62, vcc
	v_pk_mul_f32 v[36:37], v[36:37], v[62:63] op_sel_hi:[1,0]
	v_pk_mul_f32 v[38:39], v[38:39], v[62:63] op_sel_hi:[1,0]
	v_pk_mul_f32 v[36:37], v[96:97], v[36:37]
	v_pk_mul_f32 v[38:39], v[98:99], v[38:39]
	v_cvt_pk_bf16_f32 v36, v36, v37
	v_cvt_pk_bf16_f32 v37, v38, v39
	global_store_dwordx2 v[60:61], v[36:37], off
	v_pk_mul_f32 v[8:9], v[8:9], v[62:63] op_sel_hi:[1,0]
	v_pk_mul_f32 v[10:11], v[10:11], v[62:63] op_sel_hi:[1,0]
	v_pk_mul_f32 v[8:9], v[100:101], v[8:9]
	v_pk_mul_f32 v[10:11], v[102:103], v[10:11]
	v_cvt_pk_bf16_f32 v8, v8, v9
	v_cvt_pk_bf16_f32 v9, v10, v11
	global_store_dwordx2 v[60:61], v[8:9], off offset:512
	v_pk_mul_f32 v[40:41], v[40:41], v[62:63] op_sel_hi:[1,0]
	v_pk_mul_f32 v[42:43], v[42:43], v[62:63] op_sel_hi:[1,0]
	v_pk_mul_f32 v[40:41], v[104:105], v[40:41]
	v_pk_mul_f32 v[42:43], v[106:107], v[42:43]
	v_cvt_pk_bf16_f32 v40, v40, v41
	v_cvt_pk_bf16_f32 v41, v42, v43
	global_store_dwordx2 v[60:61], v[40:41], off offset:1024
	v_pk_mul_f32 v[44:45], v[44:45], v[62:63] op_sel_hi:[1,0]
	v_pk_mul_f32 v[46:47], v[46:47], v[62:63] op_sel_hi:[1,0]
	v_pk_mul_f32 v[44:45], v[108:109], v[44:45]
	v_pk_mul_f32 v[46:47], v[110:111], v[46:47]
	v_cvt_pk_bf16_f32 v44, v44, v45
	v_cvt_pk_bf16_f32 v45, v46, v47
	global_store_dwordx2 v[60:61], v[44:45], off offset:1536
	v_pk_mul_f32 v[4:5], v[4:5], v[62:63] op_sel_hi:[1,0]
	v_pk_mul_f32 v[6:7], v[6:7], v[62:63] op_sel_hi:[1,0]
	v_pk_mul_f32 v[4:5], v[112:113], v[4:5]
	v_pk_mul_f32 v[6:7], v[114:115], v[6:7]
	v_cvt_pk_bf16_f32 v4, v4, v5
	v_cvt_pk_bf16_f32 v5, v6, v7
	global_store_dwordx2 v[60:61], v[4:5], off offset:2048
	v_pk_mul_f32 v[48:49], v[48:49], v[62:63] op_sel_hi:[1,0]
	v_pk_mul_f32 v[50:51], v[50:51], v[62:63] op_sel_hi:[1,0]
	v_pk_mul_f32 v[48:49], v[116:117], v[48:49]
	v_pk_mul_f32 v[50:51], v[118:119], v[50:51]
	v_cvt_pk_bf16_f32 v48, v48, v49
	v_cvt_pk_bf16_f32 v49, v50, v51
	global_store_dwordx2 v[60:61], v[48:49], off offset:2560
	v_pk_mul_f32 v[52:53], v[52:53], v[62:63] op_sel_hi:[1,0]
	v_pk_mul_f32 v[54:55], v[54:55], v[62:63] op_sel_hi:[1,0]
	v_pk_mul_f32 v[52:53], v[120:121], v[52:53]
	v_pk_mul_f32 v[54:55], v[122:123], v[54:55]
	v_cvt_pk_bf16_f32 v52, v52, v53
	v_cvt_pk_bf16_f32 v53, v54, v55
	global_store_dwordx2 v[60:61], v[52:53], off offset:3072
	v_pk_mul_f32 v[0:1], v[0:1], v[62:63] op_sel_hi:[1,0]
	v_pk_mul_f32 v[2:3], v[2:3], v[62:63] op_sel_hi:[1,0]
	v_pk_mul_f32 v[0:1], v[124:125], v[0:1]
	v_pk_mul_f32 v[2:3], v[126:127], v[2:3]
	v_cvt_pk_bf16_f32 v0, v0, v1
	v_cvt_pk_bf16_f32 v1, v2, v3
